# ret_state: stop after the last snapshot (tiles 32..35 update a state nobody reads)
# speedup vs baseline: 1.0049x; 1.0023x over previous
.LBB0_1876:
	s_cmp_eq_u32 s21, 32
	s_cbranch_scc1 .LBB0_1891
	ds_read_b64_tr_b16 v[88:89], v1 offset:0
	ds_read_b64_tr_b16 v[90:91], v1 offset:0x800
	ds_read_b64_tr_b16 v[92:93], v69 offset:0
	ds_read_b64_tr_b16 v[94:95], v69 offset:0x800
	ds_read_b64_tr_b16 v[96:97], v1 offset:0x1000
	ds_read_b64_tr_b16 v[98:99], v1 offset:0x1800
	ds_read_b64_tr_b16 v[100:101], v69 offset:0x1000
	ds_read_b64_tr_b16 v[102:103], v69 offset:0x1800
	ds_read_b64_tr_b16 v[104:105], v1 offset:0x2000
	ds_read_b64_tr_b16 v[106:107], v1 offset:0x2800
	ds_read_b64_tr_b16 v[108:109], v69 offset:0x2000
	ds_read_b64_tr_b16 v[110:111], v69 offset:0x2800
	ds_read_b64_tr_b16 v[112:113], v1 offset:0x3000
	ds_read_b64_tr_b16 v[114:115], v1 offset:0x3800
	ds_read_b64_tr_b16 v[116:117], v69 offset:0x3000
	ds_read_b64_tr_b16 v[118:119], v69 offset:0x3800
	s_waitcnt lgkmcnt(0)
	v_mov_b32_e32 v77, v76
	s_xor_b64 s[14:15], s[14:15], -1
	v_pk_mul_f32 v[16:17], v[76:77], v[16:17]
	v_pk_mul_f32 v[14:15], v[76:77], v[14:15]
	v_pk_mul_f32 v[12:13], v[76:77], v[12:13]
	v_pk_mul_f32 v[10:11], v[76:77], v[10:11]
	v_pk_mul_f32 v[8:9], v[76:77], v[8:9]
	v_pk_mul_f32 v[6:7], v[76:77], v[6:7]
	v_pk_mul_f32 v[4:5], v[76:77], v[4:5]
	v_pk_mul_f32 v[2:3], v[80:81], v[2:3]
	v_pk_mul_f32 v[32:33], v[76:77], v[32:33]
	v_pk_mul_f32 v[30:31], v[76:77], v[30:31]
	v_pk_mul_f32 v[28:29], v[76:77], v[28:29]
	v_pk_mul_f32 v[26:27], v[76:77], v[26:27]
	v_pk_mul_f32 v[24:25], v[76:77], v[24:25]
	v_pk_mul_f32 v[22:23], v[76:77], v[22:23]
	v_pk_mul_f32 v[20:21], v[76:77], v[20:21]
	v_pk_mul_f32 v[18:19], v[80:81], v[18:19]
	v_mfma_f32_32x32x16_bf16 v[2:17], v[88:91], v[92:95], v[2:17]
	s_mov_b64 s[16:17], -1
	s_cmp_lt_u32 s21, 34
	v_mfma_f32_32x32x16_bf16 v[18:33], v[96:99], v[100:103], v[18:33]
	v_mfma_f32_32x32x16_bf16 v[2:17], v[104:107], v[108:111], v[2:17]
	v_mfma_f32_32x32x16_bf16 v[18:33], v[112:115], v[116:119], v[18:33]
	s_cbranch_scc0 .LBB0_1882
	s_and_b64 vcc, exec, s[14:15]
	s_cbranch_vccz .LBB0_1879
	s_waitcnt vmcnt(4)
	s_mov_b64 s[16:17], 0
